# FFN-up epilogue: weight-load wait made unconditional before the halo stores; later vmcnt(0) that drained write-through stores removed
# speedup vs baseline: 1.0043x; 1.0043x over previous
; __device__ __forceinline__ unsigned pk2(float lo, float hi) { unsigned r; asm volatile("v_cvt_pk_bf16_f32 %0, %1, %2" : "=v"(r) : "v"(lo), "v"(hi)); return r; }
; template <int CTRL> __device__ __forceinline__ float dppz(float x) { return __builtin_bit_cast(float, __builtin_amdgcn_update_dpp(0, __builtin_bit_cast(int, x), CTRL, 0xf, 0xf, true)); }
;     __device__ __forceinline__ void fast(const f32x4 (&acc)[2][2][4][2], const pg8::Unit& u, int wr, int wc, int fr, int fq, RsCache& rsc) const {
;     ...
; #pragma unroll
;         for (int ai = 0; ai < 2; ++ai) {
;             const int rowb = u.pm * 256 + ai * 128 + wr * 64, blk = rowb >> 6;
;             f32x2 gp[4];
; #pragma unroll
;             for (int m = 0; m < 4; ++m) {
;                 const int row = rowb + m * 16 + fr; const float s = rsc.tab[ai * 64 + m * 16 + fr]; const f32x2 s2 = (f32x2){s, s};
;                 f32x2 g[4], o[4], v[4];
; #pragma unroll
;                 for (int cp = 0; cp < 4; ++cp) { const int n = cp >> 1, e0 = (cp & 1) * 2;
;                     g[cp] = (f32x2){acc[ai][0][m][n][e0], acc[ai][0][m][n][e0 + 1]} * s2; v[cp] = (f32x2){acc[ai][1][m][n][e0], acc[ai][1][m][n][e0 + 1]} * s2; }
; #pragma unroll
;                 for (int cp = 0; cp < 4; ++cp) {
;                     f32x2 p1 = (f32x2){dppz<0x111>(g[cp].x), dppz<0x111>(g[cp].y)}, p2 = (f32x2){dppz<0x112>(g[cp].x), dppz<0x112>(g[cp].y)};
;                     if (m > 0) { p1 += (f32x2){dppz<0x10F>(gp[cp].x), dppz<0x10F>(gp[cp].y)}; p2 += (f32x2){dppz<0x10E>(gp[cp].x), dppz<0x10E>(gp[cp].y)}; }
;                     const f32x2 gv = bb[cp] + w0[cp] * p2 + w1[cp] * p1 + w2[cp] * g[cp];
;                     const f32x2 ea = gv * (-1.44269504089f);
;                     f32x2 ex; ex.x = __builtin_amdgcn_exp2f(ea.x); ex.y = __builtin_amdgcn_exp2f(ea.y);
;                     const f32x2 dn = ex + 1.0f;
;                     f32x2 rc; rc.x = __builtin_amdgcn_rcpf(dn.x); rc.y = __builtin_amdgcn_rcpf(dn.y);
;                     o[cp] = (gv * rc) * v[cp];
;                 }
;                 if (m > 0 || fr >= 2) { uint4 w; w.x = pk2(o[0].x, o[0].y); w.y = pk2(o[1].x, o[1].y); w.z = pk2(o[2].x, o[2].y); w.w = pk2(o[3].x, o[3].y); *(uint4*)(act + (size_t)row * FH + ch) = w; }
.LBB0_266:
	v_add_u32_e32 v224, s3, v186
	ds_read_b32 v172, v223
	s_waitcnt lgkmcnt(0)
	v_pk_mul_f32 v[188:189], v[166:167], v[172:173] op_sel_hi:[1,0]
	v_pk_mul_f32 v[190:191], v[158:159], v[172:173] op_sel_hi:[1,0]
	v_pk_mul_f32 v[166:167], v[168:169], v[172:173] op_sel_hi:[1,0]
	v_pk_mul_f32 v[168:169], v[160:161], v[172:173] op_sel_hi:[1,0]
	v_pk_mul_f32 v[160:161], v[162:163], v[172:173] op_sel_hi:[1,0]
	v_pk_mul_f32 v[158:159], v[164:165], v[172:173] op_sel_hi:[1,0]
	v_pk_mul_f32 v[162:163], v[154:155], v[172:173] op_sel_hi:[1,0]
	v_pk_mul_f32 v[156:157], v[156:157], v[172:173] op_sel_hi:[1,0]
	v_mov_b32_dpp v192, v188 row_shr:1 row_mask:0xf bank_mask:0xf bound_ctrl:1
	v_mov_b32_dpp v193, v189 row_shr:1 row_mask:0xf bank_mask:0xf bound_ctrl:1
	v_mov_b32_dpp v194, v188 row_shr:2 row_mask:0xf bank_mask:0xf bound_ctrl:1
	v_mov_b32_dpp v195, v189 row_shr:2 row_mask:0xf bank_mask:0xf bound_ctrl:1
	v_mov_b32_dpp v196, v166 row_shr:1 row_mask:0xf bank_mask:0xf bound_ctrl:1
	v_mov_b32_dpp v197, v167 row_shr:1 row_mask:0xf bank_mask:0xf bound_ctrl:1
	v_mov_b32_dpp v198, v166 row_shr:2 row_mask:0xf bank_mask:0xf bound_ctrl:1
	v_mov_b32_dpp v199, v167 row_shr:2 row_mask:0xf bank_mask:0xf bound_ctrl:1
	v_mov_b32_dpp v200, v160 row_shr:1 row_mask:0xf bank_mask:0xf bound_ctrl:1
	v_mov_b32_dpp v201, v161 row_shr:1 row_mask:0xf bank_mask:0xf bound_ctrl:1
	v_mov_b32_dpp v202, v160 row_shr:2 row_mask:0xf bank_mask:0xf bound_ctrl:1
	v_mov_b32_dpp v203, v161 row_shr:2 row_mask:0xf bank_mask:0xf bound_ctrl:1
	v_mov_b32_dpp v154, v158 row_shr:1 row_mask:0xf bank_mask:0xf bound_ctrl:1
	v_mov_b32_dpp v155, v159 row_shr:1 row_mask:0xf bank_mask:0xf bound_ctrl:1
	v_mov_b32_dpp v164, v158 row_shr:2 row_mask:0xf bank_mask:0xf bound_ctrl:1
	v_mov_b32_dpp v165, v159 row_shr:2 row_mask:0xf bank_mask:0xf bound_ctrl:1
	s_waitcnt vmcnt(0)
	s_and_saveexec_b64 s[0:1], s[6:7]
	v_readlane_b32 s78, v254, 59
	s_cbranch_execz .LBB0_268
	v_pk_fma_f32 v[194:195], v[90:91], v[194:195], v[102:103]
	v_pk_fma_f32 v[164:165], v[72:73], v[164:165], v[76:77]
	v_pk_fma_f32 v[172:173], v[70:71], v[202:203], v[74:75]
	v_pk_fma_f32 v[198:199], v[92:93], v[198:199], v[104:105]
	v_pk_fma_f32 v[192:193], v[94:95], v[192:193], v[194:195]
	v_pk_fma_f32 v[154:155], v[60:61], v[154:155], v[164:165]
	v_pk_fma_f32 v[172:173], v[58:59], v[200:201], v[172:173]
	s_mov_b32 s2, 0xbfb8aa3b
	v_pk_fma_f32 v[196:197], v[96:97], v[196:197], v[198:199]
	v_pk_fma_f32 v[192:193], v[98:99], v[188:189], v[192:193]
	v_pk_fma_f32 v[154:155], v[68:69], v[158:159], v[154:155]
	v_pk_fma_f32 v[172:173], v[66:67], v[160:161], v[172:173]
	v_pk_fma_f32 v[196:197], v[100:101], v[166:167], v[196:197]
	v_pk_mul_f32 v[194:195], v[192:193], s[2:3] op_sel_hi:[1,0]
	v_pk_mul_f32 v[164:165], v[154:155], s[2:3] op_sel_hi:[1,0]
	v_pk_mul_f32 v[200:201], v[172:173], s[2:3] op_sel_hi:[1,0]
	v_pk_mul_f32 v[198:199], v[196:197], s[2:3] op_sel_hi:[1,0]
	v_exp_f32_e32 v194, v194
	v_exp_f32_e32 v195, v195
	v_exp_f32_e32 v164, v164
	v_exp_f32_e32 v165, v165
	v_exp_f32_e32 v200, v200
	v_exp_f32_e32 v201, v201
	v_exp_f32_e32 v198, v198
	v_exp_f32_e32 v199, v199
	v_pk_add_f32 v[194:195], v[194:195], 1.0 op_sel_hi:[1,0]
	v_pk_add_f32 v[164:165], v[164:165], 1.0 op_sel_hi:[1,0]
	v_pk_add_f32 v[200:201], v[200:201], 1.0 op_sel_hi:[1,0]
	v_pk_add_f32 v[198:199], v[198:199], 1.0 op_sel_hi:[1,0]
	v_rcp_f32_e32 v194, v194
	v_rcp_f32_e32 v195, v195
	v_rcp_f32_e32 v164, v164
	v_rcp_f32_e32 v165, v165
	v_rcp_f32_e32 v200, v200
	v_rcp_f32_e32 v201, v201
	v_rcp_f32_e32 v198, v198
	v_rcp_f32_e32 v199, v199
	v_pk_mul_f32 v[192:193], v[192:193], v[194:195]
	v_pk_mul_f32 v[154:155], v[154:155], v[164:165]
	v_readlane_b32 s8, v253, 16
	v_pk_mul_f32 v[172:173], v[172:173], v[200:201]
	v_pk_mul_f32 v[196:197], v[196:197], v[198:199]
	v_pk_mul_f32 v[192:193], v[190:191], v[192:193]
	v_pk_mul_f32 v[154:155], v[156:157], v[154:155]
	v_readlane_b32 s9, v253, 17
	v_pk_mul_f32 v[172:173], v[162:163], v[172:173]
	v_pk_mul_f32 v[196:197], v[168:169], v[196:197]
	v_cvt_pk_bf16_f32 v192, v192, v193
	s_nop 0
	v_cvt_pk_bf16_f32 v193, v196, v197
	v_cvt_pk_bf16_f32 v194, v172, v173
	v_cvt_pk_bf16_f32 v195, v154, v155
	v_mov_b64_e32 v[154:155], s[8:9]
	v_mad_i64_i32 v[154:155], s[8:9], v224, s93, v[154:155]
	v_lshl_add_u64 v[154:155], v[184:185], 1, v[154:155]
	global_store_dwordx4 v[154:155], v[192:195], off sc1

; __device__ __forceinline__ unsigned pk2(float lo, float hi) { unsigned r; asm volatile("v_cvt_pk_bf16_f32 %0, %1, %2" : "=v"(r) : "v"(lo), "v"(hi)); return r; }
; template <int CTRL> __device__ __forceinline__ float dppz(float x) { return __builtin_bit_cast(float, __builtin_amdgcn_update_dpp(0, __builtin_bit_cast(int, x), CTRL, 0xf, 0xf, true)); }
;     __device__ __forceinline__ void fast(const f32x4 (&acc)[2][2][4][2], const pg8::Unit& u, int wr, int wc, int fr, int fq, RsCache& rsc) const {
;     ...
;             for (int m = 0; m < 4; ++m) {
;                 const int row = rowb + m * 16 + fr; const float s = rsc.tab[ai * 64 + m * 16 + fr]; const f32x2 s2 = (f32x2){s, s};
;                 f32x2 g[4], o[4], v[4];
; #pragma unroll
;                 for (int cp = 0; cp < 4; ++cp) { const int n = cp >> 1, e0 = (cp & 1) * 2;
;                     g[cp] = (f32x2){acc[ai][0][m][n][e0], acc[ai][0][m][n][e0 + 1]} * s2; v[cp] = (f32x2){acc[ai][1][m][n][e0], acc[ai][1][m][n][e0 + 1]} * s2; }
; #pragma unroll
;                 for (int cp = 0; cp < 4; ++cp) {
;                     f32x2 p1 = (f32x2){dppz<0x111>(g[cp].x), dppz<0x111>(g[cp].y)}, p2 = (f32x2){dppz<0x112>(g[cp].x), dppz<0x112>(g[cp].y)};
;                     if (m > 0) { p1 += (f32x2){dppz<0x10F>(gp[cp].x), dppz<0x10F>(gp[cp].y)}; p2 += (f32x2){dppz<0x10E>(gp[cp].x), dppz<0x10E>(gp[cp].y)}; }
;                     const f32x2 gv = bb[cp] + w0[cp] * p2 + w1[cp] * p1 + w2[cp] * g[cp];
;                     const f32x2 ea = gv * (-1.44269504089f);
;                     f32x2 ex; ex.x = __builtin_amdgcn_exp2f(ea.x); ex.y = __builtin_amdgcn_exp2f(ea.y);
;                     const f32x2 dn = ex + 1.0f;
;                     f32x2 rc; rc.x = __builtin_amdgcn_rcpf(dn.x); rc.y = __builtin_amdgcn_rcpf(dn.y);
;                     o[cp] = (gv * rc) * v[cp];
;                 }
;                 if (m > 0 || fr >= 2) { uint4 w; w.x = pk2(o[0].x, o[0].y); w.y = pk2(o[1].x, o[1].y); w.z = pk2(o[2].x, o[2].y); w.w = pk2(o[3].x, o[3].y); *(uint4*)(act + (size_t)row * FH + ch) = w; }
.LBB0_270:
	s_or_b64 exec, exec, s[82:83]
	ds_read_b32 v164, v223 offset:64
	s_mov_b32 s2, 0xbfb8aa3b
	v_readlane_b32 s74, v253, 16
	s_waitcnt lgkmcnt(0)
	v_pk_mul_f32 v[162:163], v[150:151], v[164:165] op_sel_hi:[1,0]
	v_pk_mul_f32 v[168:169], v[142:143], v[164:165] op_sel_hi:[1,0]
	v_pk_mul_f32 v[142:143], v[148:149], v[164:165] op_sel_hi:[1,0]
	v_mov_b32_dpp v148, v162 row_shr:2 row_mask:0xf bank_mask:0xf bound_ctrl:1
	v_mov_b32_dpp v149, v163 row_shr:2 row_mask:0xf bank_mask:0xf bound_ctrl:1
	v_pk_mul_f32 v[150:151], v[152:153], v[164:165] op_sel_hi:[1,0]
	v_pk_mul_f32 v[152:153], v[144:145], v[164:165] op_sel_hi:[1,0]
	v_pk_mul_f32 v[144:145], v[146:147], v[164:165] op_sel_hi:[1,0]
	v_pk_mul_f32 v[138:139], v[138:139], v[164:165] op_sel_hi:[1,0]
	v_pk_mul_f32 v[140:141], v[140:141], v[164:165] op_sel_hi:[1,0]
	v_mov_b32_dpp v146, v162 row_shr:1 row_mask:0xf bank_mask:0xf bound_ctrl:1
	v_mov_b32_dpp v147, v163 row_shr:1 row_mask:0xf bank_mask:0xf bound_ctrl:1
	v_mov_b32_dpp v148, v188 row_shl:14 row_mask:0xf bank_mask:0xf
	v_mov_b32_dpp v149, v189 row_shl:14 row_mask:0xf bank_mask:0xf
	v_mov_b32_dpp v146, v188 row_shl:15 row_mask:0xf bank_mask:0xf
	v_mov_b32_dpp v147, v189 row_shl:15 row_mask:0xf bank_mask:0xf
	v_pk_fma_f32 v[148:149], v[90:91], v[148:149], v[102:103]
	v_mov_b32_dpp v164, v150 row_shr:2 row_mask:0xf bank_mask:0xf bound_ctrl:1
	v_pk_fma_f32 v[146:147], v[94:95], v[146:147], v[148:149]
	v_mov_b32_dpp v165, v151 row_shr:2 row_mask:0xf bank_mask:0xf bound_ctrl:1
	v_pk_fma_f32 v[146:147], v[98:99], v[162:163], v[146:147]
	v_readlane_b32 s75, v253, 17
	v_pk_mul_f32 v[148:149], v[146:147], s[2:3] op_sel_hi:[1,0]
	v_cmp_lt_i32_e32 vcc, 13, v186
	v_exp_f32_e32 v148, v148
	v_exp_f32_e32 v149, v149
	v_lshl_add_u64 v[156:157], v[186:187], 0, -12
	v_pk_add_f32 v[148:149], v[148:149], 1.0 op_sel_hi:[1,0]
	s_nop 0
	v_rcp_f32_e32 v148, v148
	v_rcp_f32_e32 v149, v149
	s_nop 0
	v_pk_mul_f32 v[146:147], v[146:147], v[148:149]
	s_nop 0
	v_pk_mul_f32 v[146:147], v[168:169], v[146:147]
	v_mov_b32_dpp v168, v166 row_shl:15 row_mask:0xf bank_mask:0xf bound_ctrl:1
	v_mov_b32_dpp v169, v167 row_shl:15 row_mask:0xf bank_mask:0xf bound_ctrl:1
	v_mov_b32_dpp v148, v150 row_shr:1 row_mask:0xf bank_mask:0xf bound_ctrl:1
	v_mov_b32_dpp v149, v151 row_shr:1 row_mask:0xf bank_mask:0xf bound_ctrl:1
	v_mov_b32_dpp v164, v166 row_shl:14 row_mask:0xf bank_mask:0xf
	v_mov_b32_dpp v165, v167 row_shl:14 row_mask:0xf bank_mask:0xf
	v_pk_add_f32 v[148:149], v[148:149], v[168:169]
	v_pk_fma_f32 v[164:165], v[92:93], v[164:165], v[104:105]
	v_mov_b32_dpp v166, v160 row_shl:15 row_mask:0xf bank_mask:0xf bound_ctrl:1
	v_pk_fma_f32 v[148:149], v[96:97], v[148:149], v[164:165]
	v_mov_b32_dpp v167, v161 row_shl:15 row_mask:0xf bank_mask:0xf bound_ctrl:1
	v_pk_fma_f32 v[148:149], v[100:101], v[150:151], v[148:149]
	v_mov_b32_dpp v160, v160 row_shl:14 row_mask:0xf bank_mask:0xf bound_ctrl:1
	v_pk_mul_f32 v[164:165], v[148:149], s[2:3] op_sel_hi:[1,0]
	v_mov_b32_dpp v161, v161 row_shl:14 row_mask:0xf bank_mask:0xf bound_ctrl:1
	v_exp_f32_e32 v164, v164
	v_exp_f32_e32 v165, v165
	v_cvt_pk_bf16_f32 v146, v146, v147
	s_nop 0
	v_pk_add_f32 v[164:165], v[164:165], 1.0 op_sel_hi:[1,0]
	s_nop 0
	v_rcp_f32_e32 v164, v164
	v_rcp_f32_e32 v165, v165
	s_nop 0
	v_pk_mul_f32 v[148:149], v[148:149], v[164:165]
	v_mov_b32_dpp v164, v144 row_shr:2 row_mask:0xf bank_mask:0xf bound_ctrl:1
	v_mov_b32_dpp v165, v145 row_shr:2 row_mask:0xf bank_mask:0xf bound_ctrl:1
	v_pk_mul_f32 v[148:149], v[152:153], v[148:149]
	v_mov_b32_dpp v152, v144 row_shr:1 row_mask:0xf bank_mask:0xf bound_ctrl:1
	v_mov_b32_dpp v153, v145 row_shr:1 row_mask:0xf bank_mask:0xf bound_ctrl:1
	v_pk_add_f32 v[160:161], v[164:165], v[160:161]
	v_pk_add_f32 v[152:153], v[152:153], v[166:167]
	v_pk_fma_f32 v[160:161], v[70:71], v[160:161], v[74:75]
	v_mov_b32_dpp v164, v158 row_shl:15 row_mask:0xf bank_mask:0xf bound_ctrl:1
	v_pk_fma_f32 v[152:153], v[58:59], v[152:153], v[160:161]
	v_mov_b32_dpp v165, v159 row_shl:15 row_mask:0xf bank_mask:0xf bound_ctrl:1
	v_pk_fma_f32 v[152:153], v[66:67], v[144:145], v[152:153]
	v_mov_b32_dpp v158, v158 row_shl:14 row_mask:0xf bank_mask:0xf bound_ctrl:1
	v_pk_mul_f32 v[160:161], v[152:153], s[2:3] op_sel_hi:[1,0]
	v_mov_b32_dpp v159, v159 row_shl:14 row_mask:0xf bank_mask:0xf bound_ctrl:1
	v_exp_f32_e32 v160, v160
	v_exp_f32_e32 v161, v161
	v_add_u32_e32 v166, 16, v224
	v_cvt_pk_bf16_f32 v147, v148, v149
	v_pk_add_f32 v[160:161], v[160:161], 1.0 op_sel_hi:[1,0]
	s_nop 0
	v_rcp_f32_e32 v160, v160
	v_rcp_f32_e32 v161, v161
	s_nop 0
	v_pk_mul_f32 v[152:153], v[152:153], v[160:161]
	v_mov_b32_dpp v160, v142 row_shr:2 row_mask:0xf bank_mask:0xf bound_ctrl:1
	v_mov_b32_dpp v161, v143 row_shr:2 row_mask:0xf bank_mask:0xf bound_ctrl:1
	v_pk_mul_f32 v[138:139], v[138:139], v[152:153]
	v_mov_b32_dpp v152, v142 row_shr:1 row_mask:0xf bank_mask:0xf bound_ctrl:1
	v_mov_b32_dpp v153, v143 row_shr:1 row_mask:0xf bank_mask:0xf bound_ctrl:1
	v_pk_add_f32 v[158:159], v[160:161], v[158:159]
	v_pk_add_f32 v[152:153], v[152:153], v[164:165]
	v_pk_fma_f32 v[158:159], v[72:73], v[158:159], v[76:77]
	v_cvt_pk_bf16_f32 v148, v138, v139
	v_mov_b64_e32 v[138:139], s[74:75]
	v_pk_fma_f32 v[152:153], v[60:61], v[152:153], v[158:159]
	s_nop 0
	v_pk_fma_f32 v[152:153], v[68:69], v[142:143], v[152:153]
	s_nop 0
	v_pk_mul_f32 v[158:159], v[152:153], s[2:3] op_sel_hi:[1,0]
	s_nop 0
	v_exp_f32_e32 v158, v158
	v_exp_f32_e32 v159, v159
	s_nop 0
	v_pk_add_f32 v[158:159], v[158:159], 1.0 op_sel_hi:[1,0]
	s_nop 0
	v_rcp_f32_e32 v158, v158
	v_rcp_f32_e32 v159, v159
	s_nop 0
	v_pk_mul_f32 v[152:153], v[152:153], v[158:159]
	s_nop 0
	v_pk_mul_f32 v[140:141], v[140:141], v[152:153]
	v_cvt_pk_bf16_f32 v149, v140, v141
	v_mad_i64_i32 v[140:141], s[74:75], v166, s93, v[138:139]
	v_lshl_add_u64 v[140:141], v[140:141], 0, v[154:155]
	global_store_dwordx4 v[140:141], v[146:149], off sc1
	ds_read_b32 v146, v223 offset:128
	s_waitcnt lgkmcnt(0)
; __device__ __forceinline__ unsigned pk2(float lo, float hi) { unsigned r; asm volatile("v_cvt_pk_bf16_f32 %0, %1, %2" : "=v"(r) : "v"(lo), "v"(hi)); return r; }
; template <int CTRL> __device__ __forceinline__ float dppz(float x) { return __builtin_bit_cast(float, __builtin_amdgcn_update_dpp(0, __builtin_bit_cast(int, x), CTRL, 0xf, 0xf, true)); }
;     __device__ __forceinline__ void fast(const f32x4 (&acc)[2][2][4][2], const pg8::Unit& u, int wr, int wc, int fr, int fq, RsCache& rsc) const {
;     ...
;             for (int m = 0; m < 4; ++m) {
;                 const int row = rowb + m * 16 + fr; const float s = rsc.tab[ai * 64 + m * 16 + fr]; const f32x2 s2 = (f32x2){s, s};
;                 f32x2 g[4], o[4], v[4];
; #pragma unroll
;                 for (int cp = 0; cp < 4; ++cp) { const int n = cp >> 1, e0 = (cp & 1) * 2;
;                     g[cp] = (f32x2){acc[ai][0][m][n][e0], acc[ai][0][m][n][e0 + 1]} * s2; v[cp] = (f32x2){acc[ai][1][m][n][e0], acc[ai][1][m][n][e0 + 1]} * s2; }
; #pragma unroll
;                 for (int cp = 0; cp < 4; ++cp) {
;                     f32x2 p1 = (f32x2){dppz<0x111>(g[cp].x), dppz<0x111>(g[cp].y)}, p2 = (f32x2){dppz<0x112>(g[cp].x), dppz<0x112>(g[cp].y)};
;                     if (m > 0) { p1 += (f32x2){dppz<0x10F>(gp[cp].x), dppz<0x10F>(gp[cp].y)}; p2 += (f32x2){dppz<0x10E>(gp[cp].x), dppz<0x10E>(gp[cp].y)}; }
;                     const f32x2 gv = bb[cp] + w0[cp] * p2 + w1[cp] * p1 + w2[cp] * g[cp];
;                     const f32x2 ea = gv * (-1.44269504089f);
;                     f32x2 ex; ex.x = __builtin_amdgcn_exp2f(ea.x); ex.y = __builtin_amdgcn_exp2f(ea.y);
;                     const f32x2 dn = ex + 1.0f;
;                     f32x2 rc; rc.x = __builtin_amdgcn_rcpf(dn.x); rc.y = __builtin_amdgcn_rcpf(dn.y);
;                     o[cp] = (gv * rc) * v[cp];
;                 }
;                 if (m > 0 || fr >= 2) { uint4 w; w.x = pk2(o[0].x, o[0].y); w.y = pk2(o[1].x, o[1].y); w.z = pk2(o[2].x, o[2].y); w.w = pk2(o[3].x, o[3].y); *(uint4*)(act + (size_t)row * FH + ch) = w; }
	v_pk_mul_f32 v[140:141], v[134:135], v[146:147] op_sel_hi:[1,0]
	v_pk_mul_f32 v[134:135], v[136:137], v[146:147] op_sel_hi:[1,0]
	s_nop 0
	v_mov_b32_dpp v136, v140 row_shr:2 row_mask:0xf bank_mask:0xf bound_ctrl:1
	v_mov_b32_dpp v137, v141 row_shr:2 row_mask:0xf bank_mask:0xf bound_ctrl:1
	v_pk_mul_f32 v[148:149], v[126:127], v[146:147] op_sel_hi:[1,0]
	v_pk_mul_f32 v[128:129], v[128:129], v[146:147] op_sel_hi:[1,0]
	v_pk_mul_f32 v[126:127], v[130:131], v[146:147] op_sel_hi:[1,0]
	v_pk_mul_f32 v[130:131], v[122:123], v[146:147] op_sel_hi:[1,0]
	v_pk_mul_f32 v[122:123], v[132:133], v[146:147] op_sel_hi:[1,0]
	v_pk_mul_f32 v[124:125], v[124:125], v[146:147] op_sel_hi:[1,0]
	v_mov_b32_dpp v132, v140 row_shr:1 row_mask:0xf bank_mask:0xf bound_ctrl:1
	v_mov_b32_dpp v133, v141 row_shr:1 row_mask:0xf bank_mask:0xf bound_ctrl:1
	v_mov_b32_dpp v136, v162 row_shl:14 row_mask:0xf bank_mask:0xf
	v_mov_b32_dpp v137, v163 row_shl:14 row_mask:0xf bank_mask:0xf
	v_mov_b32_dpp v132, v162 row_shl:15 row_mask:0xf bank_mask:0xf
	v_mov_b32_dpp v133, v163 row_shl:15 row_mask:0xf bank_mask:0xf
	v_pk_fma_f32 v[136:137], v[90:91], v[136:137], v[102:103]
	v_mov_b32_dpp v146, v134 row_shr:2 row_mask:0xf bank_mask:0xf bound_ctrl:1
	v_pk_fma_f32 v[132:133], v[94:95], v[132:133], v[136:137]
	v_mov_b32_dpp v147, v135 row_shr:2 row_mask:0xf bank_mask:0xf bound_ctrl:1
	v_pk_fma_f32 v[132:133], v[98:99], v[140:141], v[132:133]
	s_nop 0
	v_pk_mul_f32 v[136:137], v[132:133], s[2:3] op_sel_hi:[1,0]
	s_nop 0
	v_exp_f32_e32 v136, v136
	v_exp_f32_e32 v137, v137
	s_nop 0
	v_pk_add_f32 v[136:137], v[136:137], 1.0 op_sel_hi:[1,0]
	s_nop 0
	v_rcp_f32_e32 v136, v136
	v_rcp_f32_e32 v137, v137
	s_nop 0
	v_pk_mul_f32 v[132:133], v[132:133], v[136:137]
	s_nop 0
	v_pk_mul_f32 v[132:133], v[148:149], v[132:133]
	v_mov_b32_dpp v148, v150 row_shl:15 row_mask:0xf bank_mask:0xf bound_ctrl:1
	v_mov_b32_dpp v149, v151 row_shl:15 row_mask:0xf bank_mask:0xf bound_ctrl:1
	v_mov_b32_dpp v136, v134 row_shr:1 row_mask:0xf bank_mask:0xf bound_ctrl:1
	v_mov_b32_dpp v137, v135 row_shr:1 row_mask:0xf bank_mask:0xf bound_ctrl:1
	v_mov_b32_dpp v146, v150 row_shl:14 row_mask:0xf bank_mask:0xf
	v_mov_b32_dpp v147, v151 row_shl:14 row_mask:0xf bank_mask:0xf
	v_pk_add_f32 v[136:137], v[136:137], v[148:149]
	v_pk_fma_f32 v[146:147], v[92:93], v[146:147], v[104:105]
	v_mov_b32_dpp v148, v144 row_shl:15 row_mask:0xf bank_mask:0xf bound_ctrl:1
	v_pk_fma_f32 v[136:137], v[96:97], v[136:137], v[146:147]
	v_mov_b32_dpp v149, v145 row_shl:15 row_mask:0xf bank_mask:0xf bound_ctrl:1
	v_pk_fma_f32 v[136:137], v[100:101], v[134:135], v[136:137]
	v_mov_b32_dpp v144, v144 row_shl:14 row_mask:0xf bank_mask:0xf bound_ctrl:1
	v_pk_mul_f32 v[146:147], v[136:137], s[2:3] op_sel_hi:[1,0]
	v_mov_b32_dpp v145, v145 row_shl:14 row_mask:0xf bank_mask:0xf bound_ctrl:1
	v_exp_f32_e32 v146, v146
	v_exp_f32_e32 v147, v147
	s_nop 0
	v_pk_add_f32 v[146:147], v[146:147], 1.0 op_sel_hi:[1,0]
	s_nop 0
	v_rcp_f32_e32 v146, v146
	v_rcp_f32_e32 v147, v147
	s_nop 0
	v_pk_mul_f32 v[136:137], v[136:137], v[146:147]
	v_mov_b32_dpp v146, v126 row_shr:2 row_mask:0xf bank_mask:0xf bound_ctrl:1
	v_mov_b32_dpp v147, v127 row_shr:2 row_mask:0xf bank_mask:0xf bound_ctrl:1
	v_pk_mul_f32 v[136:137], v[128:129], v[136:137]
	v_mov_b32_dpp v128, v126 row_shr:1 row_mask:0xf bank_mask:0xf bound_ctrl:1
	v_mov_b32_dpp v129, v127 row_shr:1 row_mask:0xf bank_mask:0xf bound_ctrl:1
	v_pk_add_f32 v[144:145], v[146:147], v[144:145]
	v_pk_add_f32 v[128:129], v[128:129], v[148:149]
	v_pk_fma_f32 v[144:145], v[70:71], v[144:145], v[74:75]
	v_mov_b32_dpp v146, v142 row_shl:15 row_mask:0xf bank_mask:0xf bound_ctrl:1
	v_pk_fma_f32 v[128:129], v[58:59], v[128:129], v[144:145]
	v_mov_b32_dpp v147, v143 row_shl:15 row_mask:0xf bank_mask:0xf bound_ctrl:1
	v_pk_fma_f32 v[128:129], v[66:67], v[126:127], v[128:129]
	v_mov_b32_dpp v142, v142 row_shl:14 row_mask:0xf bank_mask:0xf bound_ctrl:1
	v_pk_mul_f32 v[144:145], v[128:129], s[2:3] op_sel_hi:[1,0]
	v_mov_b32_dpp v143, v143 row_shl:14 row_mask:0xf bank_mask:0xf bound_ctrl:1
	v_exp_f32_e32 v144, v144
	v_exp_f32_e32 v145, v145
	v_add_u32_e32 v148, 32, v224
	v_pk_add_f32 v[144:145], v[144:145], 1.0 op_sel_hi:[1,0]
	s_nop 0
	v_rcp_f32_e32 v144, v144
	v_rcp_f32_e32 v145, v145
	s_nop 0
	v_pk_mul_f32 v[128:129], v[128:129], v[144:145]
	v_mov_b32_dpp v144, v122 row_shr:2 row_mask:0xf bank_mask:0xf bound_ctrl:1
	v_mov_b32_dpp v145, v123 row_shr:2 row_mask:0xf bank_mask:0xf bound_ctrl:1
	v_pk_mul_f32 v[130:131], v[130:131], v[128:129]
	v_mov_b32_dpp v128, v122 row_shr:1 row_mask:0xf bank_mask:0xf bound_ctrl:1
	v_mov_b32_dpp v129, v123 row_shr:1 row_mask:0xf bank_mask:0xf bound_ctrl:1
	v_pk_add_f32 v[142:143], v[144:145], v[142:143]
	v_pk_add_f32 v[128:129], v[128:129], v[146:147]
	v_pk_fma_f32 v[142:143], v[72:73], v[142:143], v[76:77]
	s_nop 0
	v_pk_fma_f32 v[128:129], v[60:61], v[128:129], v[142:143]
	s_nop 0
	v_pk_fma_f32 v[128:129], v[68:69], v[122:123], v[128:129]
	s_nop 0
	v_pk_mul_f32 v[142:143], v[128:129], s[2:3] op_sel_hi:[1,0]
	s_nop 0
	v_exp_f32_e32 v142, v142
	v_exp_f32_e32 v143, v143
	s_nop 0
	v_pk_add_f32 v[142:143], v[142:143], 1.0 op_sel_hi:[1,0]
	s_nop 0
	v_rcp_f32_e32 v142, v142
	v_rcp_f32_e32 v143, v143
	s_nop 0
	v_pk_mul_f32 v[128:129], v[128:129], v[142:143]
	s_nop 0
	v_pk_mul_f32 v[124:125], v[124:125], v[128:129]
	v_cvt_pk_bf16_f32 v128, v132, v133
	v_cvt_pk_bf16_f32 v129, v136, v137
	v_cvt_pk_bf16_f32 v130, v130, v131
	v_cvt_pk_bf16_f32 v131, v124, v125
	v_mad_i64_i32 v[124:125], s[74:75], v148, s93, v[138:139]
	v_lshl_add_u64 v[124:125], v[124:125], 0, v[154:155]
	global_store_dwordx4 v[124:125], v[128:131], off sc1
	ds_read_b32 v124, v223 offset:192
	s_waitcnt lgkmcnt(0)
;     __device__ __forceinline__ void fast(const f32x4 (&acc)[2][2][4][2], const pg8::Unit& u, int wr, int wc, int fr, int fq, RsCache& rsc) const {
;     ...
;             for (int m = 0; m < 4; ++m) {
;                 const int row = rowb + m * 16 + fr; const float s = rsc.tab[ai * 64 + m * 16 + fr]; const f32x2 s2 = (f32x2){s, s};
;                 f32x2 g[4], o[4], v[4];
; #pragma unroll
;                 for (int cp = 0; cp < 4; ++cp) { const int n = cp >> 1, e0 = (cp & 1) * 2;
;                     g[cp] = (f32x2){acc[ai][0][m][n][e0], acc[ai][0][m][n][e0 + 1]} * s2; v[cp] = (f32x2){acc[ai][1][m][n][e0], acc[ai][1][m][n][e0 + 1]} * s2; }
; #pragma unroll
;                 for (int cp = 0; cp < 4; ++cp) {
;                     f32x2 p1 = (f32x2){dppz<0x111>(g[cp].x), dppz<0x111>(g[cp].y)}, p2 = (f32x2){dppz<0x112>(g[cp].x), dppz<0x112>(g[cp].y)};
;                     if (m > 0) { p1 += (f32x2){dppz<0x10F>(gp[cp].x), dppz<0x10F>(gp[cp].y)}; p2 += (f32x2){dppz<0x10E>(gp[cp].x), dppz<0x10E>(gp[cp].y)}; }
;                     const f32x2 gv = bb[cp] + w0[cp] * p2 + w1[cp] * p1 + w2[cp] * g[cp];
;                     const f32x2 ea = gv * (-1.44269504089f);
;                     f32x2 ex; ex.x = __builtin_amdgcn_exp2f(ea.x); ex.y = __builtin_amdgcn_exp2f(ea.y);
;                     const f32x2 dn = ex + 1.0f;
;                     f32x2 rc; rc.x = __builtin_amdgcn_rcpf(dn.x); rc.y = __builtin_amdgcn_rcpf(dn.y);
;                     o[cp] = (gv * rc) * v[cp];
;                 }
;                 if (m > 0 || fr >= 2) { uint4 w; w.x = pk2(o[0].x, o[0].y); w.y = pk2(o[1].x, o[1].y); w.z = pk2(o[2].x, o[2].y); w.w = pk2(o[3].x, o[3].y); *(uint4*)(act + (size_t)row * FH + ch) = w; }
;                 if (m == 0 && fr < 2) { uint4 w; w.x = pk2(g[0].x, g[0].y); w.y = pk2(g[1].x, g[1].y); w.z = pk2(g[2].x, g[2].y); w.w = pk2(g[3].x, g[3].y); *(uint4*)(sideg + ((size_t)blk * 4 + fr) * FH + ch) = w;
;                     uint4 q; q.x = pk2(v[0].x, v[0].y); q.y = pk2(v[1].x, v[1].y); q.z = pk2(v[2].x, v[2].y); q.w = pk2(v[3].x, v[3].y); *(uint4*)(sidev + ((size_t)blk * 2 + fr) * FH + ch) = q; }
;                 if (m == 3 && fr >= 14) { uint4 w; w.x = pk2(g[0].x, g[0].y); w.y = pk2(g[1].x, g[1].y); w.z = pk2(g[2].x, g[2].y); w.w = pk2(g[3].x, g[3].y); *(uint4*)(sideg + ((size_t)blk * 4 + 2 + (fr - 14)) * FH + ch) = w; }
; #pragma unroll
	v_pk_mul_f32 v[118:119], v[118:119], v[124:125] op_sel_hi:[1,0]
	v_pk_mul_f32 v[128:129], v[110:111], v[124:125] op_sel_hi:[1,0]
	v_pk_mul_f32 v[110:111], v[120:121], v[124:125] op_sel_hi:[1,0]
	v_pk_mul_f32 v[120:121], v[112:113], v[124:125] op_sel_hi:[1,0]
	v_pk_mul_f32 v[112:113], v[114:115], v[124:125] op_sel_hi:[1,0]
	v_pk_mul_f32 v[114:115], v[106:107], v[124:125] op_sel_hi:[1,0]
	v_pk_mul_f32 v[106:107], v[116:117], v[124:125] op_sel_hi:[1,0]
	v_pk_mul_f32 v[108:109], v[108:109], v[124:125] op_sel_hi:[1,0]
	v_mov_b32_dpp v124, v118 row_shr:2 row_mask:0xf bank_mask:0xf bound_ctrl:1
	v_mov_b32_dpp v125, v119 row_shr:2 row_mask:0xf bank_mask:0xf bound_ctrl:1
	v_mov_b32_dpp v116, v118 row_shr:1 row_mask:0xf bank_mask:0xf bound_ctrl:1
	v_mov_b32_dpp v117, v119 row_shr:1 row_mask:0xf bank_mask:0xf bound_ctrl:1
	v_mov_b32_dpp v124, v140 row_shl:14 row_mask:0xf bank_mask:0xf
	v_mov_b32_dpp v125, v141 row_shl:14 row_mask:0xf bank_mask:0xf
	v_mov_b32_dpp v116, v140 row_shl:15 row_mask:0xf bank_mask:0xf
	v_mov_b32_dpp v117, v141 row_shl:15 row_mask:0xf bank_mask:0xf
	v_pk_fma_f32 v[124:125], v[90:91], v[124:125], v[102:103]
	v_pk_fma_f32 v[116:117], v[94:95], v[116:117], v[124:125]
	v_pk_fma_f32 v[116:117], v[98:99], v[118:119], v[116:117]
	v_pk_mul_f32 v[124:125], v[116:117], s[2:3] op_sel_hi:[1,0]
	v_exp_f32_e32 v124, v124
	v_exp_f32_e32 v125, v125
	s_nop 0
	v_pk_add_f32 v[124:125], v[124:125], 1.0 op_sel_hi:[1,0]
	s_nop 0
	v_rcp_f32_e32 v124, v124
	v_rcp_f32_e32 v125, v125
	s_nop 0
	v_pk_mul_f32 v[116:117], v[116:117], v[124:125]
	s_nop 0
	v_pk_mul_f32 v[116:117], v[128:129], v[116:117]
	v_mov_b32_dpp v128, v110 row_shr:2 row_mask:0xf bank_mask:0xf bound_ctrl:1
	v_mov_b32_dpp v129, v111 row_shr:2 row_mask:0xf bank_mask:0xf bound_ctrl:1
	v_mov_b32_dpp v124, v110 row_shr:1 row_mask:0xf bank_mask:0xf bound_ctrl:1
	v_mov_b32_dpp v125, v111 row_shr:1 row_mask:0xf bank_mask:0xf bound_ctrl:1
	v_mov_b32_dpp v128, v134 row_shl:14 row_mask:0xf bank_mask:0xf
	v_mov_b32_dpp v129, v135 row_shl:14 row_mask:0xf bank_mask:0xf
	v_mov_b32_dpp v124, v134 row_shl:15 row_mask:0xf bank_mask:0xf
	v_mov_b32_dpp v125, v135 row_shl:15 row_mask:0xf bank_mask:0xf
	v_pk_fma_f32 v[128:129], v[92:93], v[128:129], v[104:105]
	v_mov_b32_dpp v130, v126 row_shl:15 row_mask:0xf bank_mask:0xf bound_ctrl:1
	v_pk_fma_f32 v[124:125], v[96:97], v[124:125], v[128:129]
	v_mov_b32_dpp v131, v127 row_shl:15 row_mask:0xf bank_mask:0xf bound_ctrl:1
	v_pk_fma_f32 v[124:125], v[100:101], v[110:111], v[124:125]
	v_mov_b32_dpp v126, v126 row_shl:14 row_mask:0xf bank_mask:0xf bound_ctrl:1
	v_pk_mul_f32 v[128:129], v[124:125], s[2:3] op_sel_hi:[1,0]
	v_mov_b32_dpp v127, v127 row_shl:14 row_mask:0xf bank_mask:0xf bound_ctrl:1
	v_exp_f32_e32 v128, v128
	v_exp_f32_e32 v129, v129
	s_nop 0
	v_pk_add_f32 v[128:129], v[128:129], 1.0 op_sel_hi:[1,0]
	s_nop 0
	v_rcp_f32_e32 v128, v128
	v_rcp_f32_e32 v129, v129
	s_nop 0
	v_pk_mul_f32 v[124:125], v[124:125], v[128:129]
	v_mov_b32_dpp v128, v112 row_shr:2 row_mask:0xf bank_mask:0xf bound_ctrl:1
	v_mov_b32_dpp v129, v113 row_shr:2 row_mask:0xf bank_mask:0xf bound_ctrl:1
	v_pk_mul_f32 v[120:121], v[120:121], v[124:125]
	v_mov_b32_dpp v124, v112 row_shr:1 row_mask:0xf bank_mask:0xf bound_ctrl:1
	v_mov_b32_dpp v125, v113 row_shr:1 row_mask:0xf bank_mask:0xf bound_ctrl:1
	v_pk_add_f32 v[126:127], v[128:129], v[126:127]
	v_pk_add_f32 v[124:125], v[124:125], v[130:131]
	v_pk_fma_f32 v[126:127], v[70:71], v[126:127], v[74:75]
	v_mov_b32_dpp v128, v122 row_shl:15 row_mask:0xf bank_mask:0xf bound_ctrl:1
	v_pk_fma_f32 v[124:125], v[58:59], v[124:125], v[126:127]
	v_mov_b32_dpp v129, v123 row_shl:15 row_mask:0xf bank_mask:0xf bound_ctrl:1
	v_pk_fma_f32 v[124:125], v[66:67], v[112:113], v[124:125]
	v_mov_b32_dpp v122, v122 row_shl:14 row_mask:0xf bank_mask:0xf bound_ctrl:1
	v_pk_mul_f32 v[126:127], v[124:125], s[2:3] op_sel_hi:[1,0]
	v_mov_b32_dpp v123, v123 row_shl:14 row_mask:0xf bank_mask:0xf bound_ctrl:1
	v_exp_f32_e32 v126, v126
	v_exp_f32_e32 v127, v127
	v_add_u32_e32 v130, 48, v224
	v_pk_add_f32 v[126:127], v[126:127], 1.0 op_sel_hi:[1,0]
	s_nop 0
	v_rcp_f32_e32 v126, v126
	v_rcp_f32_e32 v127, v127
	s_nop 0
	v_pk_mul_f32 v[124:125], v[124:125], v[126:127]
	v_mov_b32_dpp v126, v106 row_shr:2 row_mask:0xf bank_mask:0xf bound_ctrl:1
	v_mov_b32_dpp v127, v107 row_shr:2 row_mask:0xf bank_mask:0xf bound_ctrl:1
	v_pk_mul_f32 v[124:125], v[114:115], v[124:125]
	v_mov_b32_dpp v114, v106 row_shr:1 row_mask:0xf bank_mask:0xf bound_ctrl:1
	v_mov_b32_dpp v115, v107 row_shr:1 row_mask:0xf bank_mask:0xf bound_ctrl:1
	v_pk_add_f32 v[122:123], v[126:127], v[122:123]
	v_pk_add_f32 v[114:115], v[114:115], v[128:129]
	v_pk_fma_f32 v[122:123], v[72:73], v[122:123], v[76:77]
	s_nop 0
	v_pk_fma_f32 v[114:115], v[60:61], v[114:115], v[122:123]
	s_nop 0
	v_pk_fma_f32 v[114:115], v[68:69], v[106:107], v[114:115]
	s_nop 0
	v_pk_mul_f32 v[122:123], v[114:115], s[2:3] op_sel_hi:[1,0]
	s_nop 0
	v_exp_f32_e32 v122, v122
	v_exp_f32_e32 v123, v123
	s_nop 0
	v_pk_add_f32 v[122:123], v[122:123], 1.0 op_sel_hi:[1,0]
	s_nop 0
	v_rcp_f32_e32 v122, v122
	v_rcp_f32_e32 v123, v123
	s_nop 0
	v_pk_mul_f32 v[114:115], v[114:115], v[122:123]
	s_nop 0
	v_pk_mul_f32 v[108:109], v[108:109], v[114:115]
	v_cvt_pk_bf16_f32 v114, v116, v117
	v_cvt_pk_bf16_f32 v115, v120, v121
	v_cvt_pk_bf16_f32 v116, v124, v125
	s_nop 0
	v_cvt_pk_bf16_f32 v117, v108, v109
	v_mad_i64_i32 v[108:109], s[74:75], v130, s93, v[138:139]
	v_lshl_add_u64 v[108:109], v[108:109], 0, v[154:155]
	global_store_dwordx4 v[108:109], v[114:117], off sc1
	s_and_saveexec_b64 s[82:83], vcc
	s_cbranch_execz .LBB0_272
	v_lshl_add_u64 v[114:115], s[0:1], 0, v[156:157]
	v_readlane_b32 s0, v254, 1
	v_readlane_b32 s1, v254, 2
	v_cvt_pk_bf16_f32 v108, v118, v119
	v_cvt_pk_bf16_f32 v109, v110, v111
	v_cvt_pk_bf16_f32 v110, v112, v113
	v_cvt_pk_bf16_f32 v111, v106, v107
	s_nop 1
	v_mov_b64_e32 v[106:107], s[0:1]
	v_mad_u64_u32 v[106:107], s[0:1], v114, s93, v[106:107]
	v_mad_i32_i24 v107, v115, s93, v107
	v_lshl_add_u64 v[106:107], v[184:185], 1, v[106:107]
	global_store_dwordx4 v[106:107], v[108:111], off sc1
